# v30: v29 + unit/item loop heads aligned
# baseline (speedup 1.0000x reference)
; #define PG8_BAR __builtin_amdgcn_s_barrier()
;     ...
;         if (!has_next) break;
; #pragma unroll
;         for (int a = 0; a < 2; ++a)
; #pragma unroll
;             for (int b = 0; b < 2; ++b)
; #pragma unroll
;                 for (int m = 0; m < 4; ++m)
; #pragma unroll
;                     for (int n = 0; n < 2; ++n) acc[a][b][m][n] = (f32x4){0.f, 0.f, 0.f, 0.f};
;         cur = nxt; cA = nA; cB = nB; ++ui;
;         if constexpr (ALIGN_EPI) { if (wr == 1) PG8_BAR; }
.LBB0_153:
	s_andn2_b64 vcc, exec, s[2:3]
	s_mov_b32 s46, s10
	s_mov_b32 s24, s18
	s_mov_b64 s[28:29], s[22:23]
	s_mov_b64 s[26:27], s[20:21]
	s_cbranch_vccz .LBB0_163
	.p2align	6

; #define PG8_BAR __builtin_amdgcn_s_barrier()
;     ...
;         if (!has_next) break;
; #pragma unroll
;         for (int a = 0; a < 2; ++a)
; #pragma unroll
;             for (int b = 0; b < 2; ++b)
; #pragma unroll
;                 for (int m = 0; m < 4; ++m)
; #pragma unroll
;                     for (int n = 0; n < 2; ++n) acc[a][b][m][n] = (f32x4){0.f, 0.f, 0.f, 0.f};
;         cur = nxt; cA = nA; cB = nB; ++ui;
;         if constexpr (ALIGN_EPI) { if (wr == 1) PG8_BAR; }
.LBB0_226:
	s_andn2_b64 vcc, exec, s[2:3]
	s_mov_b32 s14, s77
	s_mov_b32 s13, s74
	s_mov_b32 s12, s75
	s_mov_b32 s36, s76
	s_mov_b64 s[52:53], s[10:11]
	s_mov_b64 s[44:45], s[8:9]
	s_cbranch_vccz .LBB0_327
	.p2align	6

; #define PG8_BAR __builtin_amdgcn_s_barrier()
;     ...
;         if (!has_next) break;
; #pragma unroll
;         for (int a = 0; a < 2; ++a)
; #pragma unroll
;             for (int b = 0; b < 2; ++b)
; #pragma unroll
;                 for (int m = 0; m < 4; ++m)
; #pragma unroll
;                     for (int n = 0; n < 2; ++n) acc[a][b][m][n] = (f32x4){0.f, 0.f, 0.f, 0.f};
;         cur = nxt; cA = nA; cB = nB; ++ui;
;         if constexpr (ALIGN_EPI) { if (wr == 1) PG8_BAR; }
.LBB0_512:
	s_andn2_b64 vcc, exec, s[2:3]
	s_mov_b32 s46, s18
	s_mov_b32 s16, s20
	s_mov_b64 s[28:29], s[24:25]
	s_mov_b64 s[26:27], s[22:23]
	s_cbranch_vccz .LBB0_528
	.p2align	6

; __device__ __forceinline__ void phase_attn(const Frame& F, int l, bool last, int ai, int na) {
;     ...
;         const float inv = 1.0f / lrun;
;         f16* op = F.Z + (size_t)(qrow0 + r32) * ZLD + Z_AQ + hq * 128;
; #pragma unroll
;         for (int dt = 0; dt < 4; ++dt)
; #pragma unroll
;             for (int g4 = 0; g4 < 4; ++g4)
;                 *(u32x2*)(op + dt * 32 + g4 * 8 + hh * 4) = (u32x2){pk_f16(oacc[dt][g4 * 4] * inv, oacc[dt][g4 * 4 + 1] * inv), pk_f16(oacc[dt][g4 * 4 + 2] * inv, oacc[dt][g4 * 4 + 3] * inv)};
.LBB0_602:
	v_div_scale_f32 v0, s[2:3], v171, v171, 1.0
	v_rcp_f32_e32 v2, v0
	v_div_scale_f32 v3, vcc, 1.0, v171, 1.0
	s_add_i32 s17, s17, s56
	v_fma_f32 v4, -v0, v2, 1.0
	v_fmac_f32_e32 v2, v4, v2
	v_mul_f32_e32 v4, v3, v2
	v_fma_f32 v5, -v0, v4, v3
	v_fmac_f32_e32 v4, v5, v2
	v_fma_f32 v0, -v0, v4, v3
	v_div_fmas_f32 v0, v0, v2, v4
	v_div_fixup_f32 v6, v0, v171, 1.0
	v_lshlrev_b32_e32 v0, 1, v164
	v_lshl_add_u64 v[2:3], v[172:173], 0, v[0:1]
	v_mul_f32_e32 v0, v64, v6
	v_mul_f32_e32 v4, v65, v6
	v_cvt_pk_f16_f32 v4, v0, v4
	v_mul_f32_e32 v0, v66, v6
	v_mul_f32_e32 v5, v67, v6
	v_cvt_pk_f16_f32 v5, v0, v5
	global_store_dwordx2 v[2:3], v[4:5], off
	v_mul_f32_e32 v0, v68, v6
	v_mul_f32_e32 v4, v69, v6
	v_cvt_pk_f16_f32 v4, v0, v4
	v_mul_f32_e32 v0, v70, v6
	v_mul_f32_e32 v5, v71, v6
	v_cvt_pk_f16_f32 v5, v0, v5
	global_store_dwordx2 v[2:3], v[4:5], off offset:16
	v_mul_f32_e32 v0, v72, v6
	v_mul_f32_e32 v4, v73, v6
	v_cvt_pk_f16_f32 v4, v0, v4
	v_mul_f32_e32 v0, v74, v6
	v_mul_f32_e32 v5, v75, v6
	v_cvt_pk_f16_f32 v5, v0, v5
	global_store_dwordx2 v[2:3], v[4:5], off offset:32
	v_mul_f32_e32 v0, v76, v6
	v_mul_f32_e32 v4, v77, v6
	v_cvt_pk_f16_f32 v4, v0, v4
	v_mul_f32_e32 v0, v78, v6
	v_mul_f32_e32 v5, v79, v6
	v_cvt_pk_f16_f32 v5, v0, v5
	global_store_dwordx2 v[2:3], v[4:5], off offset:48
	v_mul_f32_e32 v0, v48, v6
	v_mul_f32_e32 v4, v49, v6
	v_cvt_pk_f16_f32 v4, v0, v4
	v_mul_f32_e32 v0, v50, v6
	v_mul_f32_e32 v5, v51, v6
	v_cvt_pk_f16_f32 v5, v0, v5
	global_store_dwordx2 v[2:3], v[4:5], off offset:64
	v_mul_f32_e32 v0, v52, v6
	v_mul_f32_e32 v4, v53, v6
	v_cvt_pk_f16_f32 v4, v0, v4
	v_mul_f32_e32 v0, v54, v6
	v_mul_f32_e32 v5, v55, v6
	v_cvt_pk_f16_f32 v5, v0, v5
	global_store_dwordx2 v[2:3], v[4:5], off offset:80
	v_mul_f32_e32 v0, v56, v6
	v_mul_f32_e32 v4, v57, v6
	v_cvt_pk_f16_f32 v4, v0, v4
	v_mul_f32_e32 v0, v58, v6
	v_mul_f32_e32 v5, v59, v6
	v_cvt_pk_f16_f32 v5, v0, v5
	global_store_dwordx2 v[2:3], v[4:5], off offset:96
	v_mul_f32_e32 v0, v60, v6
	v_mul_f32_e32 v4, v61, v6
	v_cvt_pk_f16_f32 v4, v0, v4
	v_mul_f32_e32 v0, v62, v6
	v_mul_f32_e32 v5, v63, v6
	v_cvt_pk_f16_f32 v5, v0, v5
	global_store_dwordx2 v[2:3], v[4:5], off offset:112
	v_mul_f32_e32 v0, v32, v6
	v_mul_f32_e32 v4, v33, v6
	v_cvt_pk_f16_f32 v4, v0, v4
	v_mul_f32_e32 v0, v34, v6
	v_mul_f32_e32 v5, v35, v6
	v_cvt_pk_f16_f32 v5, v0, v5
	global_store_dwordx2 v[2:3], v[4:5], off offset:128
	v_mul_f32_e32 v0, v36, v6
	v_mul_f32_e32 v4, v37, v6
	v_cvt_pk_f16_f32 v4, v0, v4
	v_mul_f32_e32 v0, v38, v6
	v_mul_f32_e32 v5, v39, v6
	v_cvt_pk_f16_f32 v5, v0, v5
	global_store_dwordx2 v[2:3], v[4:5], off offset:144
	v_mul_f32_e32 v0, v40, v6
	v_mul_f32_e32 v4, v41, v6
	v_cvt_pk_f16_f32 v4, v0, v4
	v_mul_f32_e32 v0, v42, v6
	v_mul_f32_e32 v5, v43, v6
	v_cvt_pk_f16_f32 v5, v0, v5
	global_store_dwordx2 v[2:3], v[4:5], off offset:160
	v_mul_f32_e32 v0, v44, v6
	v_mul_f32_e32 v4, v45, v6
	v_cvt_pk_f16_f32 v4, v0, v4
	v_mul_f32_e32 v0, v46, v6
	v_mul_f32_e32 v5, v47, v6
	v_cvt_pk_f16_f32 v5, v0, v5
	global_store_dwordx2 v[2:3], v[4:5], off offset:176
	v_mul_f32_e32 v0, v16, v6
	v_mul_f32_e32 v4, v17, v6
	v_cvt_pk_f16_f32 v4, v0, v4
	v_mul_f32_e32 v0, v18, v6
	v_mul_f32_e32 v5, v19, v6
	v_cvt_pk_f16_f32 v5, v0, v5
	global_store_dwordx2 v[2:3], v[4:5], off offset:192
	v_mul_f32_e32 v0, v20, v6
	v_mul_f32_e32 v4, v21, v6
	v_cvt_pk_f16_f32 v4, v0, v4
	v_mul_f32_e32 v0, v22, v6
	v_mul_f32_e32 v5, v23, v6
	v_cvt_pk_f16_f32 v5, v0, v5
	global_store_dwordx2 v[2:3], v[4:5], off offset:208
	v_mul_f32_e32 v0, v24, v6
	v_mul_f32_e32 v4, v25, v6
	v_cvt_pk_f16_f32 v4, v0, v4
	v_mul_f32_e32 v0, v26, v6
	v_mul_f32_e32 v5, v27, v6
	v_cvt_pk_f16_f32 v5, v0, v5
	global_store_dwordx2 v[2:3], v[4:5], off offset:224
	v_mul_f32_e32 v0, v28, v6
	v_mul_f32_e32 v4, v29, v6
	v_cvt_pk_f16_f32 v4, v0, v4
	v_mul_f32_e32 v0, v30, v6
	v_mul_f32_e32 v5, v31, v6
	s_movk_i32 s36, 0x1000
	v_cvt_pk_f16_f32 v5, v0, v5
	s_cmp_ge_i32 s17, s0
	global_store_dwordx2 v[2:3], v[4:5], off offset:240
	s_cbranch_scc1 .LBB0_620
	.p2align	6

; __device__ __forceinline__ void phase_gla(const Frame& F, int l, int gi, int ng, bool last, unsigned* cw) {
;     ...
;     for (int item = gi; item < 128; item += ng) {
;         const int b = item & 7, idx = item >> 3, h = idx >> 2, dir = (idx >> 1) & 1, sl = idx & 1;
;         const float* gwp = (dir ? F.in[17] : F.in[15]) + (size_t)l * 16 * 512 + h * 128;
;         const float* gbp = (dir ? F.in[18] : F.in[16]) + (size_t)l * 512 + h * 128;
;         f16* Oout = dir ? F.OB : F.H16;
.LBB0_638:
	s_add_i32 s16, s16, s56
	s_cmpk_gt_i32 s16, 0x7f
	s_cbranch_scc1 .LBB0_681
	.p2align	6

; #define PG8_BAR __builtin_amdgcn_s_barrier()
;     ...
;         if (!has_next) break;
; #pragma unroll
;         for (int a = 0; a < 2; ++a)
; #pragma unroll
;             for (int b = 0; b < 2; ++b)
; #pragma unroll
;                 for (int m = 0; m < 4; ++m)
; #pragma unroll
;                     for (int n = 0; n < 2; ++n) acc[a][b][m][n] = (f32x4){0.f, 0.f, 0.f, 0.f};
;         cur = nxt; cA = nA; cB = nB; ++ui;
;         if constexpr (ALIGN_EPI) { if (wr == 1) PG8_BAR; }
.LBB0_744:
	s_andn2_b64 vcc, exec, s[2:3]
	s_mov_b32 s28, s57
	s_mov_b32 s0, s55
	s_mov_b32 s8, s22
	s_mov_b32 s14, s56
	s_mov_b64 s[26:27], s[44:45]
	s_mov_b64 s[10:11], s[42:43]
	s_cbranch_vccz .LBB0_769
	.p2align	6

; #define PG8_BAR __builtin_amdgcn_s_barrier()
;     ...
;         if (!has_next) break;
; #pragma unroll
;         for (int a = 0; a < 2; ++a)
; #pragma unroll
;             for (int b = 0; b < 2; ++b)
; #pragma unroll
;                 for (int m = 0; m < 4; ++m)
; #pragma unroll
;                     for (int n = 0; n < 2; ++n) acc[a][b][m][n] = (f32x4){0.f, 0.f, 0.f, 0.f};
;         cur = nxt; cA = nA; cB = nB; ++ui;
;         if constexpr (ALIGN_EPI) { if (wr == 1) PG8_BAR; }
.LBB0_784:
	s_andn2_b64 vcc, exec, s[2:3]
	s_mov_b32 s22, s57
	s_mov_b32 s0, s55
	s_mov_b32 s8, s48
	s_mov_b32 s14, s56
	s_mov_b64 s[20:21], s[52:53]
	s_mov_b64 s[10:11], s[50:51]
	s_cbranch_vccz .LBB0_809
	.p2align	6

; #define PG8_BAR __builtin_amdgcn_s_barrier()
;     ...
;         if (!has_next) break;
; #pragma unroll
;         for (int a = 0; a < 2; ++a)
; #pragma unroll
;             for (int b = 0; b < 2; ++b)
; #pragma unroll
;                 for (int m = 0; m < 4; ++m)
; #pragma unroll
;                     for (int n = 0; n < 2; ++n) acc[a][b][m][n] = (f32x4){0.f, 0.f, 0.f, 0.f};
;         cur = nxt; cA = nA; cB = nB; ++ui;
;         if constexpr (ALIGN_EPI) { if (wr == 1) PG8_BAR; }
.LBB0_872:
	s_andn2_b64 vcc, exec, s[2:3]
	s_mov_b32 s14, s64
	s_mov_b32 s0, s63
	s_mov_b32 s10, s24
	s_mov_b32 s8, s26
	s_mov_b64 s[42:43], s[30:31]
	s_mov_b64 s[36:37], s[28:29]
	s_cbranch_vccz .LBB0_901
	.p2align	6

; #define PG8_BAR __builtin_amdgcn_s_barrier()
;     ...
;         if (!has_next) break;
; #pragma unroll
;         for (int a = 0; a < 2; ++a)
; #pragma unroll
;             for (int b = 0; b < 2; ++b)
; #pragma unroll
;                 for (int m = 0; m < 4; ++m)
; #pragma unroll
;                     for (int n = 0; n < 2; ++n) acc[a][b][m][n] = (f32x4){0.f, 0.f, 0.f, 0.f};
;         cur = nxt; cA = nA; cB = nB; ++ui;
;         if constexpr (ALIGN_EPI) { if (wr == 1) PG8_BAR; }
.LBB0_1014:
	s_andn2_b64 vcc, exec, s[2:3]
	s_mov_b32 s26, s18
	s_mov_b32 s28, s20
	s_mov_b64 s[34:35], s[24:25]
	s_mov_b64 s[30:31], s[22:23]
	s_cbranch_vccz .LBB0_1024
	.p2align	6

; #define PG8_BAR __builtin_amdgcn_s_barrier()
;     ...
;         if (!has_next) break;
; #pragma unroll
;         for (int a = 0; a < 2; ++a)
; #pragma unroll
;             for (int b = 0; b < 2; ++b)
; #pragma unroll
;                 for (int m = 0; m < 4; ++m)
; #pragma unroll
;                     for (int n = 0; n < 2; ++n) acc[a][b][m][n] = (f32x4){0.f, 0.f, 0.f, 0.f};
;         cur = nxt; cA = nA; cB = nB; ++ui;
;         if constexpr (ALIGN_EPI) { if (wr == 1) PG8_BAR; }
.LBB0_1087:
	s_andn2_b64 vcc, exec, s[2:3]
	s_mov_b32 s14, s68
	s_mov_b32 s13, s65
	s_mov_b32 s12, s66
	s_mov_b32 s28, s67
	s_mov_b64 s[36:37], s[26:27]
	s_mov_b64 s[30:31], s[24:25]
	s_cbranch_vccz .LBB0_1185
	.p2align	6
